# first two DMA waits of a tile that follows the MLP-up epilogue allow its 16 stores to stay in flight (vmcnt 24)
# baseline (speedup 1.0000x reference)
.LBB0_201:
	v_writelane_b32 v248, 0, 40
	s_cmp_eq_u32 s24, 0
	v_readlane_b32 s2, v249, 36
	s_cselect_b64 s[0:1], -1, 0
	v_readlane_b32 s3, v249, 37
	s_or_b64 s[0:1], s[2:3], s[0:1]
	s_and_b64 vcc, exec, s[0:1]
	s_cbranch_vccnz .LBB0_203
	s_add_i32 s26, s24, -1
	s_cmp_eq_u32 s26, 1
	s_cselect_b64 s[0:1], -1, 0
	s_and_b64 s[2:3], s[0:1], exec
	s_movk_i32 s2, 0xc00
	s_cselect_b32 s10, s2, 0x1000
	s_lshl_b64 s[2:3], s[26:27], 19
	s_add_u32 s84, s42, s2
	s_addc_u32 s85, s43, s3
	s_cmp_eq_u32 s26, 0
	s_cselect_b64 s[2:3], -1, 0
	s_and_b64 s[4:5], s[0:1], exec
	v_readlane_b32 s4, v252, 5
	v_readlane_b32 s5, v252, 6
	s_cselect_b32 s8, s96, s4
	s_cselect_b32 s9, s97, s5
	s_and_b64 s[4:5], s[2:3], exec
	v_readlane_b32 s4, v251, 16
	v_readlane_b32 s5, v251, 17
	s_cselect_b32 s53, s5, s9
	s_cselect_b32 s52, s4, s8
	s_and_b64 s[0:1], s[0:1], exec
	s_mov_b32 s0, 0x11000
	s_cselect_b32 s4, s0, 0x1dc00
	s_and_b64 s[0:1], s[2:3], exec
	s_cselect_b32 s0, 0, s4
	s_lshl_b32 s0, s0, 2
	s_add_u32 s62, s48, s0
	s_addc_u32 s63, s49, 0
	s_lshl_b32 s0, s26, 4
	s_sub_i32 s2, 0xffffffc0, s0
	v_readlane_b32 s0, v252, 55
	v_readlane_b32 s1, v252, 56
	s_and_b64 s[0:1], s[0:1], exec
	s_cselect_b32 s0, s2, 0
	v_readlane_b32 s1, v252, 60
	s_add_i32 s0, s1, s0
	s_ashr_i32 s1, s0, 31
	s_abs_i32 s0, s0
	v_readlane_b32 s2, v250, 21
	s_mul_hi_u32 s2, s0, s2
	v_readlane_b32 s3, v250, 27
	s_mul_i32 s2, s2, s3
	s_sub_i32 s0, s0, s2
	s_sub_i32 s2, s0, s3
	s_cmp_ge_u32 s0, s3
	s_cselect_b32 s0, s2, s0
	s_sub_i32 s2, s0, s3
	s_cmp_ge_u32 s0, s3
	s_cselect_b32 s0, s2, s0
	s_xor_b32 s0, s0, s1
	s_sub_i32 s29, s0, s1
	s_movk_i32 s20, 0x100
	s_movk_i32 s35, 0x400
	s_mov_b32 s94, 5
	s_mov_b64 s[14:15], 0
	s_mov_b64 s[16:17], 0
	s_mov_b32 s26, s10

.LBB0_246:
	s_andn2_b64 vcc, exec, s[18:19]
	s_cbranch_vccnz .Lk_zero_skip
	v_readlane_b32 vcc_lo, v248, 40
	s_mov_b32 vcc_hi, 0
	v_writelane_b32 v248, 0, 40
	s_add_u32 s44, s44, 0x80
	s_addc_u32 s45, s45, 0
	s_add_u32 s23, s46, 0x100
	s_addc_u32 s48, s47, 0
	s_mov_b32 s46, 0
	s_add_i32 s49, s46, 2
	s_add_u32 s69, s44, 0x80
	s_addc_u32 s47, s45, 0
	s_add_i32 s80, 0, 0x10000
	s_cmp_eq_u32 s90, s46
	s_cselect_b32 s47, s65, s47
	s_cselect_b32 s46, s64, s69
	s_cselect_b32 s71, s67, s48
	s_cselect_b32 s70, s66, s23
	s_add_i32 s69, 0, 0x14000
	v_add_u32_e32 v140, s80, v227
	v_add_u32_e32 v152, s69, v227
	ds_read_b128 v[128:131], v140
	ds_read_b128 v[132:135], v140 offset:1024
	ds_read_b128 v[136:139], v140 offset:2048
	ds_read_b128 v[140:143], v140 offset:3072
	ds_read_b128 v[144:147], v152
	ds_read_b128 v[148:151], v152 offset:1024
	ds_read_b128 v[174:177], v152 offset:2048
	ds_read_b128 v[178:181], v152 offset:3072
	v_lshl_add_u64 v[210:211], s[44:45], 0, v[170:171]
	s_add_i32 m0, s50, 0xc000
	ds_read_b128 v[182:185], v230
	ds_read_b128 v[186:189], v230 offset:1024
	ds_read_b128 v[190:193], v230 offset:2048
	ds_read_b128 v[194:197], v230 offset:3072
	ds_read_b128 v[198:201], v230 offset:4096
	ds_read_b128 v[202:205], v230 offset:5120
	ds_read_b128 v[206:209], v230 offset:6144
	ds_read_b128 v[232:235], v230 offset:7168
	global_load_lds_dwordx4 v[210:211], off
	v_lshl_add_u64 v[210:211], s[44:45], 0, v[172:173]
	s_add_i32 m0, s50, 0xe000
	s_nop 0
	global_load_lds_dwordx4 v[210:211], off
	s_cbranch_vccnz .Lrelax_p0
	s_waitcnt vmcnt(8)
.Lrelax_b0:
	s_waitcnt lgkmcnt(0)
	s_barrier
	s_setprio 1
	s_waitcnt lgkmcnt(0)
	v_mfma_f32_16x16x32_bf16 v[16:19], v[128:131], v[182:185], 0
	v_mfma_f32_16x16x32_bf16 v[28:31], v[136:139], v[182:185], 0
	v_mfma_f32_16x16x32_bf16 v[12:15], v[128:131], v[190:193], 0
	v_mfma_f32_16x16x32_bf16 v[8:11], v[136:139], v[190:193], 0
	v_mfma_f32_16x16x32_bf16 v[124:127], v[128:131], v[198:201], 0
	v_mfma_f32_16x16x32_bf16 v[120:123], v[136:139], v[198:201], 0
	v_mfma_f32_16x16x32_bf16 v[108:111], v[128:131], v[206:209], 0
	v_mfma_f32_16x16x32_bf16 v[104:107], v[136:139], v[206:209], 0
	v_mfma_f32_16x16x32_bf16 v[16:19], v[132:135], v[186:189], v[16:19]
	v_mfma_f32_16x16x32_bf16 v[28:31], v[140:143], v[186:189], v[28:31]
	v_mfma_f32_16x16x32_bf16 v[12:15], v[132:135], v[194:197], v[12:15]
	v_mfma_f32_16x16x32_bf16 v[8:11], v[140:143], v[194:197], v[8:11]
	v_mfma_f32_16x16x32_bf16 v[124:127], v[132:135], v[202:205], v[124:127]
	v_mfma_f32_16x16x32_bf16 v[120:123], v[140:143], v[202:205], v[120:123]
	v_mfma_f32_16x16x32_bf16 v[108:111], v[132:135], v[232:235], v[108:111]
	v_mfma_f32_16x16x32_bf16 v[104:107], v[140:143], v[232:235], v[104:107]
	s_setprio 0
	s_setprio 1
	v_mfma_f32_16x16x32_bf16 v[24:27], v[144:147], v[182:185], 0
	v_mfma_f32_16x16x32_bf16 v[20:23], v[174:177], v[182:185], 0
	v_mfma_f32_16x16x32_bf16 v[4:7], v[144:147], v[190:193], 0
	v_mfma_f32_16x16x32_bf16 v[0:3], v[174:177], v[190:193], 0
	v_mfma_f32_16x16x32_bf16 v[116:119], v[144:147], v[198:201], 0
	v_mfma_f32_16x16x32_bf16 v[112:115], v[174:177], v[198:201], 0
	v_mfma_f32_16x16x32_bf16 v[100:103], v[144:147], v[206:209], 0
	v_mfma_f32_16x16x32_bf16 v[96:99], v[174:177], v[206:209], 0
	v_mfma_f32_16x16x32_bf16 v[24:27], v[148:151], v[186:189], v[24:27]
	v_mfma_f32_16x16x32_bf16 v[20:23], v[178:181], v[186:189], v[20:23]
	v_mfma_f32_16x16x32_bf16 v[4:7], v[148:151], v[194:197], v[4:7]
	v_mfma_f32_16x16x32_bf16 v[0:3], v[178:181], v[194:197], v[0:3]
	v_mfma_f32_16x16x32_bf16 v[116:119], v[148:151], v[202:205], v[116:119]
	v_mfma_f32_16x16x32_bf16 v[112:115], v[178:181], v[202:205], v[112:115]
	v_mfma_f32_16x16x32_bf16 v[100:103], v[148:151], v[232:235], v[100:103]
	v_mfma_f32_16x16x32_bf16 v[96:99], v[178:181], v[232:235], v[96:99]
	s_setprio 0
	s_barrier
	s_add_i32 s80, s80, s3
	v_lshl_add_u64 v[210:211], s[70:71], 0, v[160:161]
	s_mov_b32 m0, s80
	ds_read_b128 v[182:185], v230 offset:16384
	ds_read_b128 v[186:189], v230 offset:17408
	ds_read_b128 v[190:193], v230 offset:18432
	ds_read_b128 v[194:197], v230 offset:19456
	ds_read_b128 v[198:201], v230 offset:20480
	ds_read_b128 v[202:205], v230 offset:21504
	ds_read_b128 v[206:209], v230 offset:22528
	ds_read_b128 v[232:235], v230 offset:23552
	global_load_lds_dwordx4 v[210:211], off
	s_add_i32 m0, s80, 0x2000
	v_lshl_add_u64 v[236:237], s[70:71], 0, v[164:165]
	s_add_u32 s70, s70, s26
	s_addc_u32 s71, s71, 0
	s_add_i32 s69, s69, s3
	global_load_lds_dwordx4 v[236:237], off
	v_lshl_add_u64 v[238:239], s[70:71], 0, v[160:161]
	s_mov_b32 m0, s69
	v_lshl_add_u64 v[240:241], s[70:71], 0, v[164:165]
	global_load_lds_dwordx4 v[238:239], off
	s_add_i32 m0, s69, 0x2000
	v_lshl_add_u64 v[242:243], s[46:47], 0, v[158:159]
	global_load_lds_dwordx4 v[240:241], off
	s_mov_b32 m0, s50
	v_lshl_add_u64 v[244:245], s[46:47], 0, v[162:163]
	global_load_lds_dwordx4 v[242:243], off
	s_mov_b32 m0, s51
	s_nop 0
	global_load_lds_dwordx4 v[244:245], off
	s_cbranch_vccnz .Lrelax_p1
	s_waitcnt vmcnt(8)
.Lrelax_b1:
	s_waitcnt lgkmcnt(0)
	s_barrier
	s_setprio 1
	s_waitcnt lgkmcnt(0)
	v_mfma_f32_16x16x32_bf16 v[92:95], v[128:131], v[182:185], 0
	v_mfma_f32_16x16x32_bf16 v[88:91], v[136:139], v[182:185], 0
	v_mfma_f32_16x16x32_bf16 v[76:79], v[128:131], v[190:193], 0
	v_mfma_f32_16x16x32_bf16 v[72:75], v[136:139], v[190:193], 0
	v_mfma_f32_16x16x32_bf16 v[60:63], v[128:131], v[198:201], 0
	v_mfma_f32_16x16x32_bf16 v[56:59], v[136:139], v[198:201], 0
	v_mfma_f32_16x16x32_bf16 v[44:47], v[128:131], v[206:209], 0
	v_mfma_f32_16x16x32_bf16 v[40:43], v[136:139], v[206:209], 0
	v_mfma_f32_16x16x32_bf16 v[92:95], v[132:135], v[186:189], v[92:95]
	v_mfma_f32_16x16x32_bf16 v[88:91], v[140:143], v[186:189], v[88:91]
	v_mfma_f32_16x16x32_bf16 v[76:79], v[132:135], v[194:197], v[76:79]
	v_mfma_f32_16x16x32_bf16 v[72:75], v[140:143], v[194:197], v[72:75]
	v_mfma_f32_16x16x32_bf16 v[60:63], v[132:135], v[202:205], v[60:63]
	v_mfma_f32_16x16x32_bf16 v[56:59], v[140:143], v[202:205], v[56:59]
	v_mfma_f32_16x16x32_bf16 v[44:47], v[132:135], v[232:235], v[44:47]
	v_mfma_f32_16x16x32_bf16 v[40:43], v[140:143], v[232:235], v[40:43]
	s_setprio 0
	s_setprio 1
	v_mfma_f32_16x16x32_bf16 v[84:87], v[144:147], v[182:185], 0
	v_mfma_f32_16x16x32_bf16 v[80:83], v[174:177], v[182:185], 0
	v_mfma_f32_16x16x32_bf16 v[68:71], v[144:147], v[190:193], 0
	v_mfma_f32_16x16x32_bf16 v[64:67], v[174:177], v[190:193], 0
	v_mfma_f32_16x16x32_bf16 v[52:55], v[144:147], v[198:201], 0
	v_mfma_f32_16x16x32_bf16 v[48:51], v[174:177], v[198:201], 0
	v_mfma_f32_16x16x32_bf16 v[36:39], v[144:147], v[206:209], 0
	v_mfma_f32_16x16x32_bf16 v[32:35], v[174:177], v[206:209], 0
	v_mfma_f32_16x16x32_bf16 v[84:87], v[148:151], v[186:189], v[84:87]
	v_mfma_f32_16x16x32_bf16 v[80:83], v[178:181], v[186:189], v[80:83]
	v_mfma_f32_16x16x32_bf16 v[68:71], v[148:151], v[194:197], v[68:71]
	v_mfma_f32_16x16x32_bf16 v[64:67], v[178:181], v[194:197], v[64:67]
	v_mfma_f32_16x16x32_bf16 v[52:55], v[148:151], v[202:205], v[52:55]
	v_mfma_f32_16x16x32_bf16 v[48:51], v[178:181], v[202:205], v[48:51]
	v_mfma_f32_16x16x32_bf16 v[36:39], v[148:151], v[232:235], v[36:39]
	v_mfma_f32_16x16x32_bf16 v[32:35], v[178:181], v[232:235], v[32:35]
	s_setprio 0
	s_barrier
	s_add_i32 s69, 0, 0x18000
	s_add_i32 s70, 0, 0x1c000
	v_add_u32_e32 v140, s69, v227
	v_add_u32_e32 v152, s70, v227
	ds_read_b128 v[128:131], v140
	ds_read_b128 v[132:135], v140 offset:1024
	ds_read_b128 v[136:139], v140 offset:2048
	ds_read_b128 v[140:143], v140 offset:3072
	ds_read_b128 v[144:147], v152
	ds_read_b128 v[148:151], v152 offset:1024
	ds_read_b128 v[174:177], v152 offset:2048
	ds_read_b128 v[178:181], v152 offset:3072
	s_add_u32 s46, s46, s26
	s_addc_u32 s47, s47, 0
	s_mov_b32 m0, s8
	v_lshl_add_u64 v[246:247], s[46:47], 0, v[158:159]
	ds_read_b128 v[182:185], v230 offset:32768
	ds_read_b128 v[186:189], v230 offset:33792
	ds_read_b128 v[190:193], v230 offset:34816
	ds_read_b128 v[194:197], v230 offset:35840
	ds_read_b128 v[198:201], v230 offset:36864
	ds_read_b128 v[202:205], v230 offset:37888
	ds_read_b128 v[206:209], v230 offset:38912
	ds_read_b128 v[232:235], v230 offset:39936
	global_load_lds_dwordx4 v[246:247], off
	v_lshl_add_u64 v[246:247], s[46:47], 0, v[162:163]
	s_mov_b32 m0, s9
	s_nop 0
	global_load_lds_dwordx4 v[246:247], off
	s_waitcnt vmcnt(8)
	s_waitcnt lgkmcnt(0)
	s_barrier
	s_setprio 1
	s_waitcnt lgkmcnt(0)
	v_mfma_f32_16x16x32_bf16 v[16:19], v[128:131], v[182:185], v[16:19]
	v_mfma_f32_16x16x32_bf16 v[28:31], v[136:139], v[182:185], v[28:31]
	v_mfma_f32_16x16x32_bf16 v[12:15], v[128:131], v[190:193], v[12:15]
	v_mfma_f32_16x16x32_bf16 v[8:11], v[136:139], v[190:193], v[8:11]
	v_mfma_f32_16x16x32_bf16 v[124:127], v[128:131], v[198:201], v[124:127]
	v_mfma_f32_16x16x32_bf16 v[120:123], v[136:139], v[198:201], v[120:123]
	v_mfma_f32_16x16x32_bf16 v[108:111], v[128:131], v[206:209], v[108:111]
	v_mfma_f32_16x16x32_bf16 v[104:107], v[136:139], v[206:209], v[104:107]
	v_mfma_f32_16x16x32_bf16 v[16:19], v[132:135], v[186:189], v[16:19]
	v_mfma_f32_16x16x32_bf16 v[28:31], v[140:143], v[186:189], v[28:31]
	v_mfma_f32_16x16x32_bf16 v[12:15], v[132:135], v[194:197], v[12:15]
	v_mfma_f32_16x16x32_bf16 v[8:11], v[140:143], v[194:197], v[8:11]
	v_mfma_f32_16x16x32_bf16 v[124:127], v[132:135], v[202:205], v[124:127]
	v_mfma_f32_16x16x32_bf16 v[120:123], v[140:143], v[202:205], v[120:123]
	v_mfma_f32_16x16x32_bf16 v[108:111], v[132:135], v[232:235], v[108:111]
	v_mfma_f32_16x16x32_bf16 v[104:107], v[140:143], v[232:235], v[104:107]
	s_setprio 0
	s_setprio 1
	v_mfma_f32_16x16x32_bf16 v[24:27], v[144:147], v[182:185], v[24:27]
	v_mfma_f32_16x16x32_bf16 v[20:23], v[174:177], v[182:185], v[20:23]
	v_mfma_f32_16x16x32_bf16 v[4:7], v[144:147], v[190:193], v[4:7]
	v_mfma_f32_16x16x32_bf16 v[0:3], v[174:177], v[190:193], v[0:3]
	v_mfma_f32_16x16x32_bf16 v[116:119], v[144:147], v[198:201], v[116:119]
	v_mfma_f32_16x16x32_bf16 v[112:115], v[174:177], v[198:201], v[112:115]
	v_mfma_f32_16x16x32_bf16 v[100:103], v[144:147], v[206:209], v[100:103]
	v_mfma_f32_16x16x32_bf16 v[96:99], v[174:177], v[206:209], v[96:99]
	v_mfma_f32_16x16x32_bf16 v[24:27], v[148:151], v[186:189], v[24:27]
	v_mfma_f32_16x16x32_bf16 v[20:23], v[178:181], v[186:189], v[20:23]
	v_mfma_f32_16x16x32_bf16 v[4:7], v[148:151], v[194:197], v[4:7]
	v_mfma_f32_16x16x32_bf16 v[0:3], v[178:181], v[194:197], v[0:3]
	v_mfma_f32_16x16x32_bf16 v[116:119], v[148:151], v[202:205], v[116:119]
	v_mfma_f32_16x16x32_bf16 v[112:115], v[178:181], v[202:205], v[112:115]
	v_mfma_f32_16x16x32_bf16 v[100:103], v[148:151], v[232:235], v[100:103]
	v_mfma_f32_16x16x32_bf16 v[96:99], v[178:181], v[232:235], v[96:99]
	s_setprio 0
	s_barrier
	s_add_i32 s46, s69, s3
	v_lshl_add_u64 v[210:211], v[210:211], 0, s[6:7]
	s_mov_b32 m0, s46
	ds_read_b128 v[182:185], v230 offset:49152
	ds_read_b128 v[186:189], v230 offset:50176
	ds_read_b128 v[190:193], v230 offset:51200
	ds_read_b128 v[194:197], v230 offset:52224
	ds_read_b128 v[198:201], v230 offset:53248
	ds_read_b128 v[202:205], v230 offset:54272
	ds_read_b128 v[206:209], v230 offset:55296
	ds_read_b128 v[232:235], v230 offset:56320
	global_load_lds_dwordx4 v[210:211], off
	v_lshl_add_u64 v[210:211], v[236:237], 0, s[6:7]
	s_add_i32 m0, s46, 0x2000
	s_add_i32 s46, s70, s3
	global_load_lds_dwordx4 v[210:211], off
	v_lshl_add_u64 v[210:211], v[238:239], 0, s[6:7]
	s_mov_b32 m0, s46
	s_nop 0
	global_load_lds_dwordx4 v[210:211], off
	v_lshl_add_u64 v[210:211], v[240:241], 0, s[6:7]
	s_add_i32 m0, s46, 0x2000
	s_nop 0
	global_load_lds_dwordx4 v[210:211], off
	v_lshl_add_u64 v[210:211], v[242:243], 0, s[6:7]
	s_mov_b32 m0, s30
	s_nop 0
	global_load_lds_dwordx4 v[210:211], off
	v_lshl_add_u64 v[210:211], v[244:245], 0, s[6:7]
	s_mov_b32 m0, s31
	s_nop 0
	global_load_lds_dwordx4 v[210:211], off
	s_waitcnt vmcnt(8)
	s_waitcnt lgkmcnt(0)
	s_barrier
	s_setprio 1
	s_waitcnt lgkmcnt(0)
	v_mfma_f32_16x16x32_bf16 v[92:95], v[128:131], v[182:185], v[92:95]
	v_mfma_f32_16x16x32_bf16 v[88:91], v[136:139], v[182:185], v[88:91]
	v_mfma_f32_16x16x32_bf16 v[76:79], v[128:131], v[190:193], v[76:79]
	v_mfma_f32_16x16x32_bf16 v[72:75], v[136:139], v[190:193], v[72:75]
	v_mfma_f32_16x16x32_bf16 v[60:63], v[128:131], v[198:201], v[60:63]
	v_mfma_f32_16x16x32_bf16 v[56:59], v[136:139], v[198:201], v[56:59]
	v_mfma_f32_16x16x32_bf16 v[44:47], v[128:131], v[206:209], v[44:47]
	v_mfma_f32_16x16x32_bf16 v[40:43], v[136:139], v[206:209], v[40:43]
	v_mfma_f32_16x16x32_bf16 v[92:95], v[132:135], v[186:189], v[92:95]
	v_mfma_f32_16x16x32_bf16 v[88:91], v[140:143], v[186:189], v[88:91]
	v_mfma_f32_16x16x32_bf16 v[76:79], v[132:135], v[194:197], v[76:79]
	v_mfma_f32_16x16x32_bf16 v[72:75], v[140:143], v[194:197], v[72:75]
	v_mfma_f32_16x16x32_bf16 v[60:63], v[132:135], v[202:205], v[60:63]
	v_mfma_f32_16x16x32_bf16 v[56:59], v[140:143], v[202:205], v[56:59]
	v_mfma_f32_16x16x32_bf16 v[44:47], v[132:135], v[232:235], v[44:47]
	v_mfma_f32_16x16x32_bf16 v[40:43], v[140:143], v[232:235], v[40:43]
	s_setprio 0
	s_setprio 1
	v_mfma_f32_16x16x32_bf16 v[84:87], v[144:147], v[182:185], v[84:87]
	v_mfma_f32_16x16x32_bf16 v[80:83], v[174:177], v[182:185], v[80:83]
	v_mfma_f32_16x16x32_bf16 v[68:71], v[144:147], v[190:193], v[68:71]
	v_mfma_f32_16x16x32_bf16 v[64:67], v[174:177], v[190:193], v[64:67]
	v_mfma_f32_16x16x32_bf16 v[52:55], v[144:147], v[198:201], v[52:55]
	v_mfma_f32_16x16x32_bf16 v[48:51], v[174:177], v[198:201], v[48:51]
	v_mfma_f32_16x16x32_bf16 v[36:39], v[144:147], v[206:209], v[36:39]
	v_mfma_f32_16x16x32_bf16 v[32:35], v[174:177], v[206:209], v[32:35]
	v_mfma_f32_16x16x32_bf16 v[84:87], v[148:151], v[186:189], v[84:87]
	v_mfma_f32_16x16x32_bf16 v[80:83], v[178:181], v[186:189], v[80:83]
	v_mfma_f32_16x16x32_bf16 v[68:71], v[148:151], v[194:197], v[68:71]
	v_mfma_f32_16x16x32_bf16 v[64:67], v[178:181], v[194:197], v[64:67]
	v_mfma_f32_16x16x32_bf16 v[52:55], v[148:151], v[202:205], v[52:55]
	v_mfma_f32_16x16x32_bf16 v[48:51], v[178:181], v[202:205], v[48:51]
	v_mfma_f32_16x16x32_bf16 v[36:39], v[148:151], v[232:235], v[36:39]
	v_mfma_f32_16x16x32_bf16 v[32:35], v[178:181], v[232:235], v[32:35]
	s_setprio 0
	s_barrier
	s_add_u32 s44, s44, 0x100
	s_addc_u32 s45, s45, 0
	s_add_u32 s23, s23, 0x100
	s_addc_u32 s48, s48, 0
	s_cmp_ge_u32 s49, s88
	s_mov_b32 s46, s49
	s_cbranch_scc1 .LBB0_249

.Lrelax_p0:
	s_waitcnt vmcnt(24)
	s_branch .Lrelax_b0

.Lepi1_fast:
	s_add_i32 s23, s22, s62
	v_lshl_add_u32 v184, v226, 2, s23
	ds_read_b128 v[140:143], v184 offset:1024
	ds_read_b128 v[136:139], v184 offset:1040
	ds_read_b128 v[132:135], v184 offset:1536
	ds_read_b128 v[128:131], v184 offset:1552
	s_lshl_b32 s23, s91, 2
	s_add_i32 s23, s22, s23
	v_lshl_add_u32 v152, v157, 2, s23
	ds_read_b32 v144, v152
	ds_read_b32 v146, v152 offset:64
	ds_read_b32 v148, v152 offset:128
	ds_read_b32 v150, v152 offset:192
	ds_read_b32 v176, v152 offset:512
	ds_read_b32 v178, v152 offset:576
	ds_read_b32 v180, v152 offset:640
	ds_read_b32 v182, v152 offset:704
	v_mul_lo_u32 v185, v174, s10
	v_lshl_or_b32 v184, s56, 8, v228
	v_add_lshl_u32 v184, v185, v184, 1
	s_mov_b64 s[22:23], s[78:79]
	s_lshl_b32 s46, s10, 5
	s_waitcnt lgkmcnt(0)
	v_fmamk_f32 v144, v144, 0x3a800000, v214
	v_fmamk_f32 v146, v146, 0x3a800000, v214
	v_fmamk_f32 v148, v148, 0x3a800000, v214
	v_fmamk_f32 v150, v150, 0x3a800000, v214
	v_fmamk_f32 v176, v176, 0x3a800000, v214
	v_fmamk_f32 v178, v178, 0x3a800000, v214
	v_fmamk_f32 v180, v180, 0x3a800000, v214
	v_fmamk_f32 v182, v182, 0x3a800000, v214
	v_rsq_f32_e32 v144, v144
	v_rsq_f32_e32 v146, v146
	v_rsq_f32_e32 v148, v148
	v_rsq_f32_e32 v150, v150
	v_rsq_f32_e32 v176, v176
	v_rsq_f32_e32 v178, v178
	v_rsq_f32_e32 v180, v180
	v_rsq_f32_e32 v182, v182
	v_pk_fma_f32 v[16:17], v[16:17], v[144:145], v[140:141] op_sel_hi:[1,0,1]
	v_pk_fma_f32 v[18:19], v[18:19], v[144:145], v[142:143] op_sel_hi:[1,0,1]
	v_pk_fma_f32 v[28:29], v[28:29], v[144:145], v[136:137] op_sel_hi:[1,0,1]
	v_pk_fma_f32 v[30:31], v[30:31], v[144:145], v[138:139] op_sel_hi:[1,0,1]
	v_max_f32_e32 v16, 0, v16
	v_max_f32_e32 v17, 0, v17
	v_max_f32_e32 v18, 0, v18
	v_max_f32_e32 v19, 0, v19
	v_max_f32_e32 v28, 0, v28
	v_max_f32_e32 v29, 0, v29
	v_max_f32_e32 v30, 0, v30
	v_max_f32_e32 v31, 0, v31
	v_pk_mul_f32 v[16:17], v[16:17], v[16:17]
	v_pk_mul_f32 v[18:19], v[18:19], v[18:19]
	v_pk_mul_f32 v[28:29], v[28:29], v[28:29]
	v_pk_mul_f32 v[30:31], v[30:31], v[30:31]
	v_cvt_pk_bf16_f32 v16, v16, v17
	v_cvt_pk_bf16_f32 v17, v18, v19
	v_cvt_pk_bf16_f32 v18, v28, v29
	v_cvt_pk_bf16_f32 v19, v30, v31
	global_store_dwordx4 v184, v[16:19], s[22:23]
	v_pk_fma_f32 v[24:25], v[24:25], v[144:145], v[132:133] op_sel_hi:[1,0,1]
	v_pk_fma_f32 v[26:27], v[26:27], v[144:145], v[134:135] op_sel_hi:[1,0,1]
	v_pk_fma_f32 v[20:21], v[20:21], v[144:145], v[128:129] op_sel_hi:[1,0,1]
	v_pk_fma_f32 v[22:23], v[22:23], v[144:145], v[130:131] op_sel_hi:[1,0,1]
	v_max_f32_e32 v24, 0, v24
	v_max_f32_e32 v25, 0, v25
	v_max_f32_e32 v26, 0, v26
	v_max_f32_e32 v27, 0, v27
	v_max_f32_e32 v20, 0, v20
	v_max_f32_e32 v21, 0, v21
	v_max_f32_e32 v22, 0, v22
	v_max_f32_e32 v23, 0, v23
	v_pk_mul_f32 v[24:25], v[24:25], v[24:25]
	v_pk_mul_f32 v[26:27], v[26:27], v[26:27]
	v_pk_mul_f32 v[20:21], v[20:21], v[20:21]
	v_pk_mul_f32 v[22:23], v[22:23], v[22:23]
	v_cvt_pk_bf16_f32 v24, v24, v25
	v_cvt_pk_bf16_f32 v25, v26, v27
	v_cvt_pk_bf16_f32 v26, v20, v21
	v_cvt_pk_bf16_f32 v27, v22, v23
	global_store_dwordx4 v184, v[24:27], s[22:23] offset:256
	s_add_u32 s22, s22, s46
	s_addc_u32 s23, s23, 0
	v_pk_fma_f32 v[12:13], v[12:13], v[146:147], v[140:141] op_sel_hi:[1,0,1]
	v_pk_fma_f32 v[14:15], v[14:15], v[146:147], v[142:143] op_sel_hi:[1,0,1]
	v_pk_fma_f32 v[8:9], v[8:9], v[146:147], v[136:137] op_sel_hi:[1,0,1]
	v_pk_fma_f32 v[10:11], v[10:11], v[146:147], v[138:139] op_sel_hi:[1,0,1]
	v_max_f32_e32 v12, 0, v12
	v_max_f32_e32 v13, 0, v13
	v_max_f32_e32 v14, 0, v14
	v_max_f32_e32 v15, 0, v15
	v_max_f32_e32 v8, 0, v8
	v_max_f32_e32 v9, 0, v9
	v_max_f32_e32 v10, 0, v10
	v_max_f32_e32 v11, 0, v11
	v_pk_mul_f32 v[12:13], v[12:13], v[12:13]
	v_pk_mul_f32 v[14:15], v[14:15], v[14:15]
	v_pk_mul_f32 v[8:9], v[8:9], v[8:9]
	v_pk_mul_f32 v[10:11], v[10:11], v[10:11]
	v_cvt_pk_bf16_f32 v12, v12, v13
	v_cvt_pk_bf16_f32 v13, v14, v15
	v_cvt_pk_bf16_f32 v14, v8, v9
	v_cvt_pk_bf16_f32 v15, v10, v11
	global_store_dwordx4 v184, v[12:15], s[22:23]
	v_pk_fma_f32 v[4:5], v[4:5], v[146:147], v[132:133] op_sel_hi:[1,0,1]
	v_pk_fma_f32 v[6:7], v[6:7], v[146:147], v[134:135] op_sel_hi:[1,0,1]
	v_pk_fma_f32 v[0:1], v[0:1], v[146:147], v[128:129] op_sel_hi:[1,0,1]
	v_pk_fma_f32 v[2:3], v[2:3], v[146:147], v[130:131] op_sel_hi:[1,0,1]
	v_max_f32_e32 v4, 0, v4
	v_max_f32_e32 v5, 0, v5
	v_max_f32_e32 v6, 0, v6
	v_max_f32_e32 v7, 0, v7
	v_max_f32_e32 v0, 0, v0
	v_max_f32_e32 v1, 0, v1
	v_max_f32_e32 v2, 0, v2
	v_max_f32_e32 v3, 0, v3
	v_pk_mul_f32 v[4:5], v[4:5], v[4:5]
	v_pk_mul_f32 v[6:7], v[6:7], v[6:7]
	v_pk_mul_f32 v[0:1], v[0:1], v[0:1]
	v_pk_mul_f32 v[2:3], v[2:3], v[2:3]
	v_cvt_pk_bf16_f32 v4, v4, v5
	v_cvt_pk_bf16_f32 v5, v6, v7
	v_cvt_pk_bf16_f32 v6, v0, v1
	v_cvt_pk_bf16_f32 v7, v2, v3
	global_store_dwordx4 v184, v[4:7], s[22:23] offset:256
	s_add_u32 s22, s22, s46
	s_addc_u32 s23, s23, 0
	v_pk_fma_f32 v[124:125], v[124:125], v[148:149], v[140:141] op_sel_hi:[1,0,1]
	v_pk_fma_f32 v[126:127], v[126:127], v[148:149], v[142:143] op_sel_hi:[1,0,1]
	v_pk_fma_f32 v[120:121], v[120:121], v[148:149], v[136:137] op_sel_hi:[1,0,1]
	v_pk_fma_f32 v[122:123], v[122:123], v[148:149], v[138:139] op_sel_hi:[1,0,1]
	v_max_f32_e32 v124, 0, v124
	v_max_f32_e32 v125, 0, v125
	v_max_f32_e32 v126, 0, v126
	v_max_f32_e32 v127, 0, v127
	v_max_f32_e32 v120, 0, v120
	v_max_f32_e32 v121, 0, v121
	v_max_f32_e32 v122, 0, v122
	v_max_f32_e32 v123, 0, v123
	v_pk_mul_f32 v[124:125], v[124:125], v[124:125]
	v_pk_mul_f32 v[126:127], v[126:127], v[126:127]
	v_pk_mul_f32 v[120:121], v[120:121], v[120:121]
	v_pk_mul_f32 v[122:123], v[122:123], v[122:123]
	v_cvt_pk_bf16_f32 v124, v124, v125
	v_cvt_pk_bf16_f32 v125, v126, v127
	v_cvt_pk_bf16_f32 v126, v120, v121
	v_cvt_pk_bf16_f32 v127, v122, v123
	global_store_dwordx4 v184, v[124:127], s[22:23]
	v_pk_fma_f32 v[116:117], v[116:117], v[148:149], v[132:133] op_sel_hi:[1,0,1]
	v_pk_fma_f32 v[118:119], v[118:119], v[148:149], v[134:135] op_sel_hi:[1,0,1]
	v_pk_fma_f32 v[112:113], v[112:113], v[148:149], v[128:129] op_sel_hi:[1,0,1]
	v_pk_fma_f32 v[114:115], v[114:115], v[148:149], v[130:131] op_sel_hi:[1,0,1]
	v_max_f32_e32 v116, 0, v116
	v_max_f32_e32 v117, 0, v117
	v_max_f32_e32 v118, 0, v118
	v_max_f32_e32 v119, 0, v119
	v_max_f32_e32 v112, 0, v112
	v_max_f32_e32 v113, 0, v113
	v_max_f32_e32 v114, 0, v114
	v_max_f32_e32 v115, 0, v115
	v_pk_mul_f32 v[116:117], v[116:117], v[116:117]
	v_pk_mul_f32 v[118:119], v[118:119], v[118:119]
	v_pk_mul_f32 v[112:113], v[112:113], v[112:113]
	v_pk_mul_f32 v[114:115], v[114:115], v[114:115]
	v_cvt_pk_bf16_f32 v116, v116, v117
	v_cvt_pk_bf16_f32 v117, v118, v119
	v_cvt_pk_bf16_f32 v118, v112, v113
	v_cvt_pk_bf16_f32 v119, v114, v115
	global_store_dwordx4 v184, v[116:119], s[22:23] offset:256
	s_add_u32 s22, s22, s46
	s_addc_u32 s23, s23, 0
	v_pk_fma_f32 v[108:109], v[108:109], v[150:151], v[140:141] op_sel_hi:[1,0,1]
	v_pk_fma_f32 v[110:111], v[110:111], v[150:151], v[142:143] op_sel_hi:[1,0,1]
	v_pk_fma_f32 v[104:105], v[104:105], v[150:151], v[136:137] op_sel_hi:[1,0,1]
	v_pk_fma_f32 v[106:107], v[106:107], v[150:151], v[138:139] op_sel_hi:[1,0,1]
	v_max_f32_e32 v108, 0, v108
	v_max_f32_e32 v109, 0, v109
	v_max_f32_e32 v110, 0, v110
	v_max_f32_e32 v111, 0, v111
	v_max_f32_e32 v104, 0, v104
	v_max_f32_e32 v105, 0, v105
	v_max_f32_e32 v106, 0, v106
	v_max_f32_e32 v107, 0, v107
	v_pk_mul_f32 v[108:109], v[108:109], v[108:109]
	v_pk_mul_f32 v[110:111], v[110:111], v[110:111]
	v_pk_mul_f32 v[104:105], v[104:105], v[104:105]
	v_pk_mul_f32 v[106:107], v[106:107], v[106:107]
	v_cvt_pk_bf16_f32 v108, v108, v109
	v_cvt_pk_bf16_f32 v109, v110, v111
	v_cvt_pk_bf16_f32 v110, v104, v105
	v_cvt_pk_bf16_f32 v111, v106, v107
	global_store_dwordx4 v184, v[108:111], s[22:23]
	v_pk_fma_f32 v[100:101], v[100:101], v[150:151], v[132:133] op_sel_hi:[1,0,1]
	v_pk_fma_f32 v[102:103], v[102:103], v[150:151], v[134:135] op_sel_hi:[1,0,1]
	v_pk_fma_f32 v[96:97], v[96:97], v[150:151], v[128:129] op_sel_hi:[1,0,1]
	v_pk_fma_f32 v[98:99], v[98:99], v[150:151], v[130:131] op_sel_hi:[1,0,1]
	v_max_f32_e32 v100, 0, v100
	v_max_f32_e32 v101, 0, v101
	v_max_f32_e32 v102, 0, v102
	v_max_f32_e32 v103, 0, v103
	v_max_f32_e32 v96, 0, v96
	v_max_f32_e32 v97, 0, v97
	v_max_f32_e32 v98, 0, v98
	v_max_f32_e32 v99, 0, v99
	v_pk_mul_f32 v[100:101], v[100:101], v[100:101]
	v_pk_mul_f32 v[102:103], v[102:103], v[102:103]
	v_pk_mul_f32 v[96:97], v[96:97], v[96:97]
	v_pk_mul_f32 v[98:99], v[98:99], v[98:99]
	v_cvt_pk_bf16_f32 v100, v100, v101
	v_cvt_pk_bf16_f32 v101, v102, v103
	v_cvt_pk_bf16_f32 v102, v96, v97
	v_cvt_pk_bf16_f32 v103, v98, v99
	global_store_dwordx4 v184, v[100:103], s[22:23] offset:256
	s_add_u32 s22, s22, s46
	s_addc_u32 s23, s23, 0
	s_add_u32 s22, s22, s46
	s_addc_u32 s23, s23, 0
	s_add_u32 s22, s22, s46
	s_addc_u32 s23, s23, 0
	s_add_u32 s22, s22, s46
	s_addc_u32 s23, s23, 0
	s_add_u32 s22, s22, s46
	s_addc_u32 s23, s23, 0
	v_pk_fma_f32 v[92:93], v[92:93], v[176:177], v[140:141] op_sel_hi:[1,0,1]
	v_pk_fma_f32 v[94:95], v[94:95], v[176:177], v[142:143] op_sel_hi:[1,0,1]
	v_pk_fma_f32 v[88:89], v[88:89], v[176:177], v[136:137] op_sel_hi:[1,0,1]
	v_pk_fma_f32 v[90:91], v[90:91], v[176:177], v[138:139] op_sel_hi:[1,0,1]
	v_max_f32_e32 v92, 0, v92
	v_max_f32_e32 v93, 0, v93
	v_max_f32_e32 v94, 0, v94
	v_max_f32_e32 v95, 0, v95
	v_max_f32_e32 v88, 0, v88
	v_max_f32_e32 v89, 0, v89
	v_max_f32_e32 v90, 0, v90
	v_max_f32_e32 v91, 0, v91
	v_pk_mul_f32 v[92:93], v[92:93], v[92:93]
	v_pk_mul_f32 v[94:95], v[94:95], v[94:95]
	v_pk_mul_f32 v[88:89], v[88:89], v[88:89]
	v_pk_mul_f32 v[90:91], v[90:91], v[90:91]
	v_cvt_pk_bf16_f32 v92, v92, v93
	v_cvt_pk_bf16_f32 v93, v94, v95
	v_cvt_pk_bf16_f32 v94, v88, v89
	v_cvt_pk_bf16_f32 v95, v90, v91
	global_store_dwordx4 v184, v[92:95], s[22:23]
	v_pk_fma_f32 v[84:85], v[84:85], v[176:177], v[132:133] op_sel_hi:[1,0,1]
	v_pk_fma_f32 v[86:87], v[86:87], v[176:177], v[134:135] op_sel_hi:[1,0,1]
	v_pk_fma_f32 v[80:81], v[80:81], v[176:177], v[128:129] op_sel_hi:[1,0,1]
	v_pk_fma_f32 v[82:83], v[82:83], v[176:177], v[130:131] op_sel_hi:[1,0,1]
	v_max_f32_e32 v84, 0, v84
	v_max_f32_e32 v85, 0, v85
	v_max_f32_e32 v86, 0, v86
	v_max_f32_e32 v87, 0, v87
	v_max_f32_e32 v80, 0, v80
	v_max_f32_e32 v81, 0, v81
	v_max_f32_e32 v82, 0, v82
	v_max_f32_e32 v83, 0, v83
	v_pk_mul_f32 v[84:85], v[84:85], v[84:85]
	v_pk_mul_f32 v[86:87], v[86:87], v[86:87]
	v_pk_mul_f32 v[80:81], v[80:81], v[80:81]
	v_pk_mul_f32 v[82:83], v[82:83], v[82:83]
	v_cvt_pk_bf16_f32 v84, v84, v85
	v_cvt_pk_bf16_f32 v85, v86, v87
	v_cvt_pk_bf16_f32 v86, v80, v81
	v_cvt_pk_bf16_f32 v87, v82, v83
	global_store_dwordx4 v184, v[84:87], s[22:23] offset:256
	s_add_u32 s22, s22, s46
	s_addc_u32 s23, s23, 0
	v_pk_fma_f32 v[76:77], v[76:77], v[178:179], v[140:141] op_sel_hi:[1,0,1]
	v_pk_fma_f32 v[78:79], v[78:79], v[178:179], v[142:143] op_sel_hi:[1,0,1]
	v_pk_fma_f32 v[72:73], v[72:73], v[178:179], v[136:137] op_sel_hi:[1,0,1]
	v_pk_fma_f32 v[74:75], v[74:75], v[178:179], v[138:139] op_sel_hi:[1,0,1]
	v_max_f32_e32 v76, 0, v76
	v_max_f32_e32 v77, 0, v77
	v_max_f32_e32 v78, 0, v78
	v_max_f32_e32 v79, 0, v79
	v_max_f32_e32 v72, 0, v72
	v_max_f32_e32 v73, 0, v73
	v_max_f32_e32 v74, 0, v74
	v_max_f32_e32 v75, 0, v75
	v_pk_mul_f32 v[76:77], v[76:77], v[76:77]
	v_pk_mul_f32 v[78:79], v[78:79], v[78:79]
	v_pk_mul_f32 v[72:73], v[72:73], v[72:73]
	v_pk_mul_f32 v[74:75], v[74:75], v[74:75]
	v_cvt_pk_bf16_f32 v76, v76, v77
	v_cvt_pk_bf16_f32 v77, v78, v79
	v_cvt_pk_bf16_f32 v78, v72, v73
	v_cvt_pk_bf16_f32 v79, v74, v75
	global_store_dwordx4 v184, v[76:79], s[22:23]
	v_pk_fma_f32 v[68:69], v[68:69], v[178:179], v[132:133] op_sel_hi:[1,0,1]
	v_pk_fma_f32 v[70:71], v[70:71], v[178:179], v[134:135] op_sel_hi:[1,0,1]
	v_pk_fma_f32 v[64:65], v[64:65], v[178:179], v[128:129] op_sel_hi:[1,0,1]
	v_pk_fma_f32 v[66:67], v[66:67], v[178:179], v[130:131] op_sel_hi:[1,0,1]
	v_max_f32_e32 v68, 0, v68
	v_max_f32_e32 v69, 0, v69
	v_max_f32_e32 v70, 0, v70
	v_max_f32_e32 v71, 0, v71
	v_max_f32_e32 v64, 0, v64
	v_max_f32_e32 v65, 0, v65
	v_max_f32_e32 v66, 0, v66
	v_max_f32_e32 v67, 0, v67
	v_pk_mul_f32 v[68:69], v[68:69], v[68:69]
	v_pk_mul_f32 v[70:71], v[70:71], v[70:71]
	v_pk_mul_f32 v[64:65], v[64:65], v[64:65]
	v_pk_mul_f32 v[66:67], v[66:67], v[66:67]
	v_cvt_pk_bf16_f32 v68, v68, v69
	v_cvt_pk_bf16_f32 v69, v70, v71
	v_cvt_pk_bf16_f32 v70, v64, v65
	v_cvt_pk_bf16_f32 v71, v66, v67
	global_store_dwordx4 v184, v[68:71], s[22:23] offset:256
	s_add_u32 s22, s22, s46
	s_addc_u32 s23, s23, 0
	v_pk_fma_f32 v[60:61], v[60:61], v[180:181], v[140:141] op_sel_hi:[1,0,1]
	v_pk_fma_f32 v[62:63], v[62:63], v[180:181], v[142:143] op_sel_hi:[1,0,1]
	v_pk_fma_f32 v[56:57], v[56:57], v[180:181], v[136:137] op_sel_hi:[1,0,1]
	v_pk_fma_f32 v[58:59], v[58:59], v[180:181], v[138:139] op_sel_hi:[1,0,1]
	v_max_f32_e32 v60, 0, v60
	v_max_f32_e32 v61, 0, v61
	v_max_f32_e32 v62, 0, v62
	v_max_f32_e32 v63, 0, v63
	v_max_f32_e32 v56, 0, v56
	v_max_f32_e32 v57, 0, v57
	v_max_f32_e32 v58, 0, v58
	v_max_f32_e32 v59, 0, v59
	v_pk_mul_f32 v[60:61], v[60:61], v[60:61]
	v_pk_mul_f32 v[62:63], v[62:63], v[62:63]
	v_pk_mul_f32 v[56:57], v[56:57], v[56:57]
	v_pk_mul_f32 v[58:59], v[58:59], v[58:59]
	v_cvt_pk_bf16_f32 v60, v60, v61
	v_cvt_pk_bf16_f32 v61, v62, v63
	v_cvt_pk_bf16_f32 v62, v56, v57
	v_cvt_pk_bf16_f32 v63, v58, v59
	global_store_dwordx4 v184, v[60:63], s[22:23]
	v_pk_fma_f32 v[52:53], v[52:53], v[180:181], v[132:133] op_sel_hi:[1,0,1]
	v_pk_fma_f32 v[54:55], v[54:55], v[180:181], v[134:135] op_sel_hi:[1,0,1]
	v_pk_fma_f32 v[48:49], v[48:49], v[180:181], v[128:129] op_sel_hi:[1,0,1]
	v_pk_fma_f32 v[50:51], v[50:51], v[180:181], v[130:131] op_sel_hi:[1,0,1]
	v_max_f32_e32 v52, 0, v52
	v_max_f32_e32 v53, 0, v53
	v_max_f32_e32 v54, 0, v54
	v_max_f32_e32 v55, 0, v55
	v_max_f32_e32 v48, 0, v48
	v_max_f32_e32 v49, 0, v49
	v_max_f32_e32 v50, 0, v50
	v_max_f32_e32 v51, 0, v51
	v_pk_mul_f32 v[52:53], v[52:53], v[52:53]
	v_pk_mul_f32 v[54:55], v[54:55], v[54:55]
	v_pk_mul_f32 v[48:49], v[48:49], v[48:49]
	v_pk_mul_f32 v[50:51], v[50:51], v[50:51]
	v_cvt_pk_bf16_f32 v52, v52, v53
	v_cvt_pk_bf16_f32 v53, v54, v55
	v_cvt_pk_bf16_f32 v54, v48, v49
	v_cvt_pk_bf16_f32 v55, v50, v51
	global_store_dwordx4 v184, v[52:55], s[22:23] offset:256
	s_add_u32 s22, s22, s46
	s_addc_u32 s23, s23, 0
	v_pk_fma_f32 v[44:45], v[44:45], v[182:183], v[140:141] op_sel_hi:[1,0,1]
	v_pk_fma_f32 v[46:47], v[46:47], v[182:183], v[142:143] op_sel_hi:[1,0,1]
	v_pk_fma_f32 v[40:41], v[40:41], v[182:183], v[136:137] op_sel_hi:[1,0,1]
	v_pk_fma_f32 v[42:43], v[42:43], v[182:183], v[138:139] op_sel_hi:[1,0,1]
	v_max_f32_e32 v44, 0, v44
	v_max_f32_e32 v45, 0, v45
	v_max_f32_e32 v46, 0, v46
	v_max_f32_e32 v47, 0, v47
	v_max_f32_e32 v40, 0, v40
	v_max_f32_e32 v41, 0, v41
	v_max_f32_e32 v42, 0, v42
	v_max_f32_e32 v43, 0, v43
	v_pk_mul_f32 v[44:45], v[44:45], v[44:45]
	v_pk_mul_f32 v[46:47], v[46:47], v[46:47]
	v_pk_mul_f32 v[40:41], v[40:41], v[40:41]
	v_pk_mul_f32 v[42:43], v[42:43], v[42:43]
	v_cvt_pk_bf16_f32 v44, v44, v45
	v_cvt_pk_bf16_f32 v45, v46, v47
	v_cvt_pk_bf16_f32 v46, v40, v41
	v_cvt_pk_bf16_f32 v47, v42, v43
	global_store_dwordx4 v184, v[44:47], s[22:23]
	v_pk_fma_f32 v[36:37], v[36:37], v[182:183], v[132:133] op_sel_hi:[1,0,1]
	v_pk_fma_f32 v[38:39], v[38:39], v[182:183], v[134:135] op_sel_hi:[1,0,1]
	v_pk_fma_f32 v[32:33], v[32:33], v[182:183], v[128:129] op_sel_hi:[1,0,1]
	v_pk_fma_f32 v[34:35], v[34:35], v[182:183], v[130:131] op_sel_hi:[1,0,1]
	v_max_f32_e32 v36, 0, v36
	v_max_f32_e32 v37, 0, v37
	v_max_f32_e32 v38, 0, v38
	v_max_f32_e32 v39, 0, v39
	v_max_f32_e32 v32, 0, v32
	v_max_f32_e32 v33, 0, v33
	v_max_f32_e32 v34, 0, v34
	v_max_f32_e32 v35, 0, v35
	v_pk_mul_f32 v[36:37], v[36:37], v[36:37]
	v_pk_mul_f32 v[38:39], v[38:39], v[38:39]
	v_pk_mul_f32 v[32:33], v[32:33], v[32:33]
	v_pk_mul_f32 v[34:35], v[34:35], v[34:35]
	v_cvt_pk_bf16_f32 v36, v36, v37
	v_cvt_pk_bf16_f32 v37, v38, v39
	v_cvt_pk_bf16_f32 v38, v32, v33
	v_cvt_pk_bf16_f32 v39, v34, v35
	global_store_dwordx4 v184, v[36:39], s[22:23] offset:256
	v_writelane_b32 v248, 1, 40
	s_branch .LBB0_461
